# epilogue yield s_sleep 40
# speedup vs baseline: 1.0014x; 1.0012x over previous
.LBB0_1163:
	s_ashr_i32 s17, s54, 3
	s_mul_hi_i32 s19, s17, 0x9000
	s_mul_i32 s17, s17, 0x9000
	s_add_u32 s26, s10, s17
	s_addc_u32 s27, s11, s19
	v_lshl_add_u64 v[162:163], s[26:27], 0, v[160:161]
	global_load_dwordx4 v[64:67], v[162:163], off
	v_readlane_b32 s26, v255, 5
	v_readlane_b32 s27, v255, 6
	s_lshl_b32 s17, s54, 8
	v_add_u32_e32 v194, s17, v151
	v_lshl_add_u64 v[166:167], s[26:27], 0, v[160:161]
	v_readlane_b32 s26, v255, 9
	v_readlane_b32 s27, v255, 10
	v_ashrrev_i32_e32 v195, 31, v194
	v_lshl_add_u64 v[212:213], v[194:195], 3, s[12:13]
	v_lshl_add_u64 v[168:169], s[26:27], 0, v[160:161]
	v_lshlrev_b64 v[214:215], 12, v[194:195]
	v_lshl_add_u64 v[214:215], s[0:1], 0, v[214:215]
	v_lshl_add_u64 v[214:215], v[214:215], 0, v[160:161]
	s_waitcnt vmcnt(0)
	v_pk_add_f32 v[178:179], v[66:67], 1.0 op_sel_hi:[1,0]
	v_pk_add_f32 v[180:181], v[64:65], 1.0 op_sel_hi:[1,0]
	global_load_dwordx4 v[84:87], v[166:167], off
	global_load_dwordx4 v[64:67], v[168:169], off
	s_waitcnt vmcnt(0)
	v_pk_mul_f32 v[190:191], v[66:67], s[58:59] op_sel_hi:[1,0]
	v_pk_mul_f32 v[192:193], v[64:65], s[58:59] op_sel_hi:[1,0]
	global_load_dwordx4 v[64:67], v[162:163], off offset:64
	s_waitcnt vmcnt(0)
	v_pk_add_f32 v[174:175], v[66:67], 1.0 op_sel_hi:[1,0]
	v_pk_add_f32 v[176:177], v[64:65], 1.0 op_sel_hi:[1,0]
	global_load_dwordx4 v[72:75], v[166:167], off offset:64
	global_load_dwordx4 v[64:67], v[168:169], off offset:64
	s_waitcnt vmcnt(0)
	v_pk_mul_f32 v[186:187], v[66:67], s[58:59] op_sel_hi:[1,0]
	v_pk_mul_f32 v[188:189], v[64:65], s[58:59] op_sel_hi:[1,0]
	global_load_dwordx4 v[64:67], v[162:163], off offset:512
	s_waitcnt vmcnt(0)
	v_pk_add_f32 v[170:171], v[66:67], 1.0 op_sel_hi:[1,0]
	v_pk_add_f32 v[172:173], v[64:65], 1.0 op_sel_hi:[1,0]
	global_load_dwordx4 v[68:71], v[166:167], off offset:512
	global_load_dwordx4 v[64:67], v[168:169], off offset:512
	s_waitcnt vmcnt(0)
	v_pk_mul_f32 v[182:183], v[66:67], s[58:59] op_sel_hi:[1,0]
	v_pk_mul_f32 v[184:185], v[64:65], s[58:59] op_sel_hi:[1,0]
	global_load_dwordx4 v[64:67], v[162:163], off offset:576
	s_waitcnt vmcnt(0)
	v_pk_add_f32 v[162:163], v[66:67], 1.0 op_sel_hi:[1,0]
	v_pk_add_f32 v[164:165], v[64:65], 1.0 op_sel_hi:[1,0]
	global_load_dwordx4 v[64:67], v[166:167], off offset:576
	global_load_dwordx4 v[232:235], v[168:169], off offset:576
	s_waitcnt vmcnt(0)
	v_pk_mul_f32 v[166:167], v[234:235], s[58:59] op_sel_hi:[1,0]
	global_load_dwordx2 v[212:213], v[212:213], off
	v_pk_mul_f32 v[168:169], v[232:233], s[58:59] op_sel_hi:[1,0]
	global_load_dwordx4 v[232:235], v[214:215], off
	global_load_dwordx4 v[236:239], v[214:215], off offset:64
	global_load_dwordx4 v[240:243], v[214:215], off offset:512
	global_load_dwordx4 v[244:247], v[214:215], off offset:576
	s_waitcnt vmcnt(4)
	v_mul_f32_e32 v216, 0x3fb504f3, v213
	s_waitcnt vmcnt(3)
	v_sub_f32_e32 v219, v233, v212
	v_sub_f32_e32 v218, v232, v212
	v_sub_f32_e32 v233, v235, v212
	v_sub_f32_e32 v232, v234, v212
	v_pk_mul_f32 v[232:233], v[232:233], v[216:217] op_sel_hi:[1,0]
	v_pk_mul_f32 v[218:219], v[218:219], v[216:217] op_sel_hi:[1,0]
	v_pk_fma_f32 v[232:233], v[86:87], v[232:233], v[190:191]
	v_pk_fma_f32 v[218:219], v[84:85], v[218:219], v[192:193]
	v_pk_fma_f32 v[142:143], v[142:143], v[178:179], v[232:233]
	v_pk_fma_f32 v[140:141], v[140:141], v[180:181], v[218:219]
	global_store_dwordx4 v[214:215], v[140:143], off
	s_waitcnt vmcnt(3)
	s_nop 0
	v_sub_f32_e32 v141, v237, v212
	v_sub_f32_e32 v140, v236, v212
	v_sub_f32_e32 v143, v239, v212
	v_sub_f32_e32 v142, v238, v212
	v_pk_mul_f32 v[142:143], v[142:143], v[216:217] op_sel_hi:[1,0]
	v_pk_mul_f32 v[140:141], v[140:141], v[216:217] op_sel_hi:[1,0]
	v_pk_fma_f32 v[142:143], v[74:75], v[142:143], v[186:187]
	v_pk_fma_f32 v[140:141], v[72:73], v[140:141], v[188:189]
	v_pk_fma_f32 v[138:139], v[138:139], v[174:175], v[142:143]
	v_pk_fma_f32 v[136:137], v[136:137], v[176:177], v[140:141]
	global_store_dwordx4 v[214:215], v[136:139], off offset:64
	s_waitcnt vmcnt(3)
	s_nop 0
	v_sub_f32_e32 v137, v241, v212
	v_sub_f32_e32 v136, v240, v212
	v_sub_f32_e32 v139, v243, v212
	v_sub_f32_e32 v138, v242, v212
	v_pk_mul_f32 v[138:139], v[216:217], v[138:139] op_sel_hi:[0,1]
	v_pk_mul_f32 v[136:137], v[216:217], v[136:137] op_sel_hi:[0,1]
	v_pk_fma_f32 v[136:137], v[68:69], v[136:137], v[184:185]
	v_pk_fma_f32 v[138:139], v[70:71], v[138:139], v[182:183]
	v_pk_fma_f32 v[132:133], v[132:133], v[172:173], v[136:137]
	v_pk_fma_f32 v[134:135], v[134:135], v[170:171], v[138:139]
	global_store_dwordx4 v[214:215], v[132:135], off offset:512
	s_waitcnt vmcnt(3)
	s_nop 0
	v_sub_f32_e32 v133, v245, v212
	v_sub_f32_e32 v132, v244, v212
	v_sub_f32_e32 v135, v247, v212
	v_sub_f32_e32 v134, v246, v212
	v_pk_mul_f32 v[134:135], v[216:217], v[134:135] op_sel_hi:[0,1]
	v_pk_mul_f32 v[132:133], v[216:217], v[132:133] op_sel_hi:[0,1]
	v_pk_fma_f32 v[132:133], v[64:65], v[132:133], v[168:169]
	v_pk_fma_f32 v[134:135], v[66:67], v[134:135], v[166:167]
	v_pk_fma_f32 v[128:129], v[128:129], v[164:165], v[132:133]
	v_pk_fma_f32 v[130:131], v[130:131], v[162:163], v[134:135]
	global_store_dwordx4 v[214:215], v[128:131], off offset:576
	s_and_b64 vcc, exec, s[6:7]
	s_cbranch_vccnz .Lmy_epi_w0
	s_sleep 40
.Lmy_epi_w0:
	s_nop 1
	v_add_u32_e32 v128, s17, v226
	v_ashrrev_i32_e32 v129, 31, v128
	v_lshl_add_u64 v[130:131], v[128:129], 3, s[12:13]
	global_load_dwordx2 v[212:213], v[130:131], off
	v_lshlrev_b64 v[128:129], 12, v[128:129]
	v_lshl_add_u64 v[128:129], s[0:1], 0, v[128:129]
	v_lshl_add_u64 v[214:215], v[128:129], 0, v[160:161]
	global_load_dwordx4 v[128:131], v[214:215], off
	global_load_dwordx4 v[132:135], v[214:215], off offset:64
	global_load_dwordx4 v[136:139], v[214:215], off offset:512
	global_load_dwordx4 v[140:143], v[214:215], off offset:576
	s_waitcnt vmcnt(4)
	v_mul_f32_e32 v216, 0x3fb504f3, v213
	s_waitcnt vmcnt(3)
	v_sub_f32_e32 v129, v129, v212
	v_sub_f32_e32 v128, v128, v212
	v_sub_f32_e32 v131, v131, v212
	v_sub_f32_e32 v130, v130, v212
	v_pk_mul_f32 v[130:131], v[130:131], v[216:217] op_sel_hi:[1,0]
	v_pk_mul_f32 v[128:129], v[128:129], v[216:217] op_sel_hi:[1,0]
	v_pk_fma_f32 v[130:131], v[86:87], v[130:131], v[190:191]
	v_pk_fma_f32 v[128:129], v[84:85], v[128:129], v[192:193]
	v_pk_fma_f32 v[126:127], v[126:127], v[178:179], v[130:131]
	v_pk_fma_f32 v[124:125], v[124:125], v[180:181], v[128:129]
	global_store_dwordx4 v[214:215], v[124:127], off
	s_waitcnt vmcnt(3)
	s_nop 0
	v_sub_f32_e32 v125, v133, v212
	v_sub_f32_e32 v124, v132, v212
	v_sub_f32_e32 v127, v135, v212
	v_sub_f32_e32 v126, v134, v212
	v_pk_mul_f32 v[126:127], v[126:127], v[216:217] op_sel_hi:[1,0]
	v_pk_mul_f32 v[124:125], v[124:125], v[216:217] op_sel_hi:[1,0]
	v_pk_fma_f32 v[126:127], v[74:75], v[126:127], v[186:187]
	v_pk_fma_f32 v[124:125], v[72:73], v[124:125], v[188:189]
	v_pk_fma_f32 v[122:123], v[122:123], v[174:175], v[126:127]
	v_pk_fma_f32 v[120:121], v[120:121], v[176:177], v[124:125]
	global_store_dwordx4 v[214:215], v[120:123], off offset:64
	s_waitcnt vmcnt(3)
	s_nop 0
	v_sub_f32_e32 v121, v137, v212
	v_sub_f32_e32 v120, v136, v212
	v_sub_f32_e32 v123, v139, v212
	v_sub_f32_e32 v122, v138, v212
	v_pk_mul_f32 v[122:123], v[216:217], v[122:123] op_sel_hi:[0,1]
	v_pk_mul_f32 v[120:121], v[216:217], v[120:121] op_sel_hi:[0,1]
	v_pk_fma_f32 v[120:121], v[68:69], v[120:121], v[184:185]
	v_pk_fma_f32 v[122:123], v[70:71], v[122:123], v[182:183]
	v_pk_fma_f32 v[116:117], v[116:117], v[172:173], v[120:121]
	v_pk_fma_f32 v[118:119], v[118:119], v[170:171], v[122:123]
	global_store_dwordx4 v[214:215], v[116:119], off offset:512
	s_waitcnt vmcnt(3)
	s_nop 0
	v_sub_f32_e32 v117, v141, v212
	v_sub_f32_e32 v116, v140, v212
	v_sub_f32_e32 v119, v143, v212
	v_sub_f32_e32 v118, v142, v212
	v_pk_mul_f32 v[118:119], v[216:217], v[118:119] op_sel_hi:[0,1]
	v_pk_mul_f32 v[116:117], v[216:217], v[116:117] op_sel_hi:[0,1]
	v_pk_fma_f32 v[116:117], v[64:65], v[116:117], v[168:169]
	v_pk_fma_f32 v[118:119], v[66:67], v[118:119], v[166:167]
	v_pk_fma_f32 v[112:113], v[112:113], v[164:165], v[116:117]
	v_pk_fma_f32 v[114:115], v[114:115], v[162:163], v[118:119]
	global_store_dwordx4 v[214:215], v[112:115], off offset:576
	s_and_b64 vcc, exec, s[6:7]
	s_cbranch_vccnz .Lmy_epi_w1
	s_sleep 40
.Lmy_epi_w1:
	s_nop 1
	v_add_u32_e32 v112, s17, v227
	v_ashrrev_i32_e32 v113, 31, v112
	v_lshl_add_u64 v[114:115], v[112:113], 3, s[12:13]
	global_load_dwordx2 v[128:129], v[114:115], off
	v_lshlrev_b64 v[112:113], 12, v[112:113]
	v_lshl_add_u64 v[112:113], s[0:1], 0, v[112:113]
	v_lshl_add_u64 v[130:131], v[112:113], 0, v[160:161]
	global_load_dwordx4 v[112:115], v[130:131], off
	global_load_dwordx4 v[116:119], v[130:131], off offset:64
	global_load_dwordx4 v[120:123], v[130:131], off offset:512
	global_load_dwordx4 v[124:127], v[130:131], off offset:576
	s_waitcnt vmcnt(4)
	v_mul_f32_e32 v132, 0x3fb504f3, v129
	s_waitcnt vmcnt(3)
	v_sub_f32_e32 v113, v113, v128
	v_sub_f32_e32 v112, v112, v128
	v_sub_f32_e32 v115, v115, v128
	v_sub_f32_e32 v114, v114, v128
	v_pk_mul_f32 v[114:115], v[114:115], v[132:133] op_sel_hi:[1,0]
	v_pk_mul_f32 v[112:113], v[112:113], v[132:133] op_sel_hi:[1,0]
	v_pk_fma_f32 v[114:115], v[86:87], v[114:115], v[190:191]
	v_pk_fma_f32 v[112:113], v[84:85], v[112:113], v[192:193]
	v_pk_fma_f32 v[110:111], v[110:111], v[178:179], v[114:115]
	v_pk_fma_f32 v[108:109], v[108:109], v[180:181], v[112:113]
	global_store_dwordx4 v[130:131], v[108:111], off
	s_waitcnt vmcnt(3)
	s_nop 0
	v_sub_f32_e32 v109, v117, v128
	v_sub_f32_e32 v108, v116, v128
	v_sub_f32_e32 v111, v119, v128
	v_sub_f32_e32 v110, v118, v128
	v_pk_mul_f32 v[110:111], v[110:111], v[132:133] op_sel_hi:[1,0]
	v_pk_mul_f32 v[108:109], v[108:109], v[132:133] op_sel_hi:[1,0]
	v_pk_fma_f32 v[110:111], v[74:75], v[110:111], v[186:187]
	v_pk_fma_f32 v[108:109], v[72:73], v[108:109], v[188:189]
	v_pk_fma_f32 v[106:107], v[106:107], v[174:175], v[110:111]
	v_pk_fma_f32 v[104:105], v[104:105], v[176:177], v[108:109]
	global_store_dwordx4 v[130:131], v[104:107], off offset:64
	s_waitcnt vmcnt(3)
	s_nop 0
	v_sub_f32_e32 v105, v121, v128
	v_sub_f32_e32 v104, v120, v128
	v_sub_f32_e32 v107, v123, v128
	v_sub_f32_e32 v106, v122, v128
	v_pk_mul_f32 v[106:107], v[132:133], v[106:107] op_sel_hi:[0,1]
	v_pk_mul_f32 v[104:105], v[132:133], v[104:105] op_sel_hi:[0,1]
	v_pk_fma_f32 v[104:105], v[68:69], v[104:105], v[184:185]
	v_pk_fma_f32 v[106:107], v[70:71], v[106:107], v[182:183]
	v_pk_fma_f32 v[100:101], v[100:101], v[172:173], v[104:105]
	v_pk_fma_f32 v[102:103], v[102:103], v[170:171], v[106:107]
	global_store_dwordx4 v[130:131], v[100:103], off offset:512
	s_waitcnt vmcnt(3)
	s_nop 0
	v_sub_f32_e32 v101, v125, v128
	v_sub_f32_e32 v100, v124, v128
	v_sub_f32_e32 v103, v127, v128
	v_sub_f32_e32 v102, v126, v128
	v_pk_mul_f32 v[102:103], v[132:133], v[102:103] op_sel_hi:[0,1]
	v_pk_mul_f32 v[100:101], v[132:133], v[100:101] op_sel_hi:[0,1]
	v_pk_fma_f32 v[100:101], v[64:65], v[100:101], v[168:169]
	v_pk_fma_f32 v[102:103], v[66:67], v[102:103], v[166:167]
	v_pk_fma_f32 v[96:97], v[96:97], v[164:165], v[100:101]
	v_pk_fma_f32 v[98:99], v[98:99], v[162:163], v[102:103]
	global_store_dwordx4 v[130:131], v[96:99], off offset:576
	s_and_b64 vcc, exec, s[6:7]
	s_cbranch_vccnz .Lmy_epi_w2
	s_sleep 40
.Lmy_epi_w2:
	s_nop 1
	v_add_u32_e32 v96, s17, v228
	v_ashrrev_i32_e32 v97, 31, v96
	v_lshl_add_u64 v[98:99], v[96:97], 3, s[12:13]
	global_load_dwordx2 v[112:113], v[98:99], off
	v_lshlrev_b64 v[96:97], 12, v[96:97]
	v_lshl_add_u64 v[96:97], s[0:1], 0, v[96:97]
	v_lshl_add_u64 v[114:115], v[96:97], 0, v[160:161]
	global_load_dwordx4 v[96:99], v[114:115], off
	global_load_dwordx4 v[100:103], v[114:115], off offset:64
	global_load_dwordx4 v[104:107], v[114:115], off offset:512
	global_load_dwordx4 v[108:111], v[114:115], off offset:576
	s_waitcnt vmcnt(4)
	v_mul_f32_e32 v116, 0x3fb504f3, v113
	s_waitcnt vmcnt(3)
	v_sub_f32_e32 v97, v97, v112
	v_sub_f32_e32 v96, v96, v112
	v_sub_f32_e32 v99, v99, v112
	v_sub_f32_e32 v98, v98, v112
	v_pk_mul_f32 v[98:99], v[98:99], v[116:117] op_sel_hi:[1,0]
	v_pk_mul_f32 v[96:97], v[96:97], v[116:117] op_sel_hi:[1,0]
	v_pk_fma_f32 v[98:99], v[86:87], v[98:99], v[190:191]
	v_pk_fma_f32 v[96:97], v[84:85], v[96:97], v[192:193]
	v_pk_fma_f32 v[94:95], v[94:95], v[178:179], v[98:99]
	v_pk_fma_f32 v[92:93], v[92:93], v[180:181], v[96:97]
	global_store_dwordx4 v[114:115], v[92:95], off
	s_waitcnt vmcnt(3)
	s_nop 0
	v_sub_f32_e32 v93, v101, v112
	v_sub_f32_e32 v92, v100, v112
	v_sub_f32_e32 v95, v103, v112
	v_sub_f32_e32 v94, v102, v112
	v_pk_mul_f32 v[94:95], v[94:95], v[116:117] op_sel_hi:[1,0]
	v_pk_mul_f32 v[92:93], v[92:93], v[116:117] op_sel_hi:[1,0]
	v_pk_fma_f32 v[94:95], v[74:75], v[94:95], v[186:187]
	v_pk_fma_f32 v[92:93], v[72:73], v[92:93], v[188:189]
	v_pk_fma_f32 v[90:91], v[90:91], v[174:175], v[94:95]
	v_pk_fma_f32 v[88:89], v[88:89], v[176:177], v[92:93]
	global_store_dwordx4 v[114:115], v[88:91], off offset:64
	s_waitcnt vmcnt(3)
	s_nop 0
	v_sub_f32_e32 v89, v105, v112
	v_sub_f32_e32 v88, v104, v112
	v_sub_f32_e32 v91, v107, v112
	v_sub_f32_e32 v90, v106, v112
	v_pk_mul_f32 v[90:91], v[116:117], v[90:91] op_sel_hi:[0,1]
	v_pk_mul_f32 v[88:89], v[116:117], v[88:89] op_sel_hi:[0,1]
	v_pk_fma_f32 v[88:89], v[68:69], v[88:89], v[184:185]
	v_pk_fma_f32 v[90:91], v[70:71], v[90:91], v[182:183]
	v_pk_fma_f32 v[80:81], v[80:81], v[172:173], v[88:89]
	v_pk_fma_f32 v[82:83], v[82:83], v[170:171], v[90:91]
	global_store_dwordx4 v[114:115], v[80:83], off offset:512
	s_waitcnt vmcnt(3)
	s_nop 0
	v_sub_f32_e32 v81, v109, v112
	v_sub_f32_e32 v80, v108, v112
	v_sub_f32_e32 v83, v111, v112
	v_sub_f32_e32 v82, v110, v112
	v_pk_mul_f32 v[82:83], v[116:117], v[82:83] op_sel_hi:[0,1]
	v_pk_mul_f32 v[80:81], v[116:117], v[80:81] op_sel_hi:[0,1]
	v_pk_fma_f32 v[80:81], v[64:65], v[80:81], v[168:169]
	v_pk_fma_f32 v[82:83], v[66:67], v[82:83], v[166:167]
	v_pk_fma_f32 v[76:77], v[76:77], v[164:165], v[80:81]
	v_pk_fma_f32 v[78:79], v[78:79], v[162:163], v[82:83]
	global_store_dwordx4 v[114:115], v[76:79], off offset:576
	s_and_b64 vcc, exec, s[6:7]
	s_cbranch_vccnz .Lmy_epi_w3
	s_sleep 40
.Lmy_epi_w3:
	s_nop 1
	v_add_u32_e32 v76, 0x80, v194
	v_ashrrev_i32_e32 v77, 31, v76
	v_lshl_add_u64 v[78:79], v[76:77], 3, s[12:13]
	global_load_dwordx2 v[96:97], v[78:79], off
	v_lshlrev_b64 v[76:77], 12, v[76:77]
	v_lshl_add_u64 v[76:77], s[0:1], 0, v[76:77]
	v_lshl_add_u64 v[98:99], v[76:77], 0, v[160:161]
	global_load_dwordx4 v[76:79], v[98:99], off
	global_load_dwordx4 v[80:83], v[98:99], off offset:64
	global_load_dwordx4 v[88:91], v[98:99], off offset:512
	global_load_dwordx4 v[92:95], v[98:99], off offset:576
	s_waitcnt vmcnt(4)
	v_mul_f32_e32 v100, 0x3fb504f3, v97
	s_waitcnt vmcnt(3)
	v_sub_f32_e32 v77, v77, v96
	v_sub_f32_e32 v76, v76, v96
	v_sub_f32_e32 v79, v79, v96
	v_sub_f32_e32 v78, v78, v96
	v_pk_mul_f32 v[78:79], v[78:79], v[100:101] op_sel_hi:[1,0]
	v_pk_mul_f32 v[76:77], v[76:77], v[100:101] op_sel_hi:[1,0]
	v_pk_fma_f32 v[78:79], v[86:87], v[78:79], v[190:191]
	v_pk_fma_f32 v[76:77], v[84:85], v[76:77], v[192:193]
	v_pk_fma_f32 v[62:63], v[62:63], v[178:179], v[78:79]
	v_pk_fma_f32 v[60:61], v[60:61], v[180:181], v[76:77]
	global_store_dwordx4 v[98:99], v[60:63], off
	s_waitcnt vmcnt(3)
	s_nop 0
	v_sub_f32_e32 v61, v81, v96
	v_sub_f32_e32 v60, v80, v96
	v_sub_f32_e32 v63, v83, v96
	v_sub_f32_e32 v62, v82, v96
	v_pk_mul_f32 v[62:63], v[62:63], v[100:101] op_sel_hi:[1,0]
	v_pk_mul_f32 v[60:61], v[60:61], v[100:101] op_sel_hi:[1,0]
	v_pk_fma_f32 v[62:63], v[74:75], v[62:63], v[186:187]
	v_pk_fma_f32 v[60:61], v[72:73], v[60:61], v[188:189]
	v_pk_fma_f32 v[58:59], v[58:59], v[174:175], v[62:63]
	v_pk_fma_f32 v[56:57], v[56:57], v[176:177], v[60:61]
	global_store_dwordx4 v[98:99], v[56:59], off offset:64
	s_waitcnt vmcnt(3)
	s_nop 0
	v_sub_f32_e32 v57, v89, v96
	v_sub_f32_e32 v56, v88, v96
	v_sub_f32_e32 v59, v91, v96
	v_sub_f32_e32 v58, v90, v96
	v_pk_mul_f32 v[58:59], v[100:101], v[58:59] op_sel_hi:[0,1]
	v_pk_mul_f32 v[56:57], v[100:101], v[56:57] op_sel_hi:[0,1]
	v_pk_fma_f32 v[56:57], v[68:69], v[56:57], v[184:185]
	v_pk_fma_f32 v[58:59], v[70:71], v[58:59], v[182:183]
	v_pk_fma_f32 v[52:53], v[52:53], v[172:173], v[56:57]
	v_pk_fma_f32 v[54:55], v[54:55], v[170:171], v[58:59]
	global_store_dwordx4 v[98:99], v[52:55], off offset:512
	s_waitcnt vmcnt(3)
	s_nop 0
	v_sub_f32_e32 v53, v93, v96
	v_sub_f32_e32 v52, v92, v96
	v_sub_f32_e32 v55, v95, v96
	v_sub_f32_e32 v54, v94, v96
	v_pk_mul_f32 v[54:55], v[100:101], v[54:55] op_sel_hi:[0,1]
	v_pk_mul_f32 v[52:53], v[100:101], v[52:53] op_sel_hi:[0,1]
	v_pk_fma_f32 v[52:53], v[64:65], v[52:53], v[168:169]
	v_pk_fma_f32 v[54:55], v[66:67], v[54:55], v[166:167]
	v_pk_fma_f32 v[48:49], v[48:49], v[164:165], v[52:53]
	v_pk_fma_f32 v[50:51], v[50:51], v[162:163], v[54:55]
	global_store_dwordx4 v[98:99], v[48:51], off offset:576
	s_and_b64 vcc, exec, s[6:7]
	s_cbranch_vccnz .Lmy_epi_w4
	s_sleep 40
.Lmy_epi_w4:
	s_nop 1
	v_add_u32_e32 v48, 0x90, v194
	v_ashrrev_i32_e32 v49, 31, v48
	v_lshl_add_u64 v[50:51], v[48:49], 3, s[12:13]
	global_load_dwordx2 v[76:77], v[50:51], off
	v_lshlrev_b64 v[48:49], 12, v[48:49]
	v_lshl_add_u64 v[48:49], s[0:1], 0, v[48:49]
	v_lshl_add_u64 v[78:79], v[48:49], 0, v[160:161]
	global_load_dwordx4 v[48:51], v[78:79], off
	global_load_dwordx4 v[52:55], v[78:79], off offset:64
	global_load_dwordx4 v[56:59], v[78:79], off offset:512
	global_load_dwordx4 v[60:63], v[78:79], off offset:576
	s_waitcnt vmcnt(4)
	v_mul_f32_e32 v80, 0x3fb504f3, v77
	s_waitcnt vmcnt(3)
	v_sub_f32_e32 v49, v49, v76
	v_sub_f32_e32 v48, v48, v76
	v_sub_f32_e32 v51, v51, v76
	v_sub_f32_e32 v50, v50, v76
	v_pk_mul_f32 v[50:51], v[50:51], v[80:81] op_sel_hi:[1,0]
	v_pk_mul_f32 v[48:49], v[48:49], v[80:81] op_sel_hi:[1,0]
	v_pk_fma_f32 v[50:51], v[86:87], v[50:51], v[190:191]
	v_pk_fma_f32 v[48:49], v[84:85], v[48:49], v[192:193]
	v_pk_fma_f32 v[46:47], v[46:47], v[178:179], v[50:51]
	v_pk_fma_f32 v[44:45], v[44:45], v[180:181], v[48:49]
	global_store_dwordx4 v[78:79], v[44:47], off
	s_waitcnt vmcnt(3)
	s_nop 0
	v_sub_f32_e32 v45, v53, v76
	v_sub_f32_e32 v44, v52, v76
	v_sub_f32_e32 v47, v55, v76
	v_sub_f32_e32 v46, v54, v76
	v_pk_mul_f32 v[46:47], v[46:47], v[80:81] op_sel_hi:[1,0]
	v_pk_mul_f32 v[44:45], v[44:45], v[80:81] op_sel_hi:[1,0]
	v_pk_fma_f32 v[46:47], v[74:75], v[46:47], v[186:187]
	v_pk_fma_f32 v[44:45], v[72:73], v[44:45], v[188:189]
	v_pk_fma_f32 v[42:43], v[42:43], v[174:175], v[46:47]
	v_pk_fma_f32 v[40:41], v[40:41], v[176:177], v[44:45]
	global_store_dwordx4 v[78:79], v[40:43], off offset:64
	s_waitcnt vmcnt(3)
	s_nop 0
	v_sub_f32_e32 v41, v57, v76
	v_sub_f32_e32 v40, v56, v76
	v_sub_f32_e32 v43, v59, v76
	v_sub_f32_e32 v42, v58, v76
	v_pk_mul_f32 v[42:43], v[80:81], v[42:43] op_sel_hi:[0,1]
	v_pk_mul_f32 v[40:41], v[80:81], v[40:41] op_sel_hi:[0,1]
	v_pk_fma_f32 v[40:41], v[68:69], v[40:41], v[184:185]
	v_pk_fma_f32 v[42:43], v[70:71], v[42:43], v[182:183]
	v_pk_fma_f32 v[36:37], v[36:37], v[172:173], v[40:41]
	v_pk_fma_f32 v[38:39], v[38:39], v[170:171], v[42:43]
	global_store_dwordx4 v[78:79], v[36:39], off offset:512
	s_waitcnt vmcnt(3)
	s_nop 0
	v_sub_f32_e32 v37, v61, v76
	v_sub_f32_e32 v36, v60, v76
	v_sub_f32_e32 v39, v63, v76
	v_sub_f32_e32 v38, v62, v76
	v_pk_mul_f32 v[38:39], v[80:81], v[38:39] op_sel_hi:[0,1]
	v_pk_mul_f32 v[36:37], v[80:81], v[36:37] op_sel_hi:[0,1]
	v_pk_fma_f32 v[36:37], v[64:65], v[36:37], v[168:169]
	v_pk_fma_f32 v[38:39], v[66:67], v[38:39], v[166:167]
	v_pk_fma_f32 v[32:33], v[32:33], v[164:165], v[36:37]
	v_pk_fma_f32 v[34:35], v[34:35], v[162:163], v[38:39]
	global_store_dwordx4 v[78:79], v[32:35], off offset:576
	s_and_b64 vcc, exec, s[6:7]
	s_cbranch_vccnz .Lmy_epi_w5
	s_sleep 40
.Lmy_epi_w5:
	s_nop 1
	v_add_u32_e32 v32, 0xa0, v194
	v_ashrrev_i32_e32 v33, 31, v32
	v_lshl_add_u64 v[34:35], v[32:33], 3, s[12:13]
	global_load_dwordx2 v[48:49], v[34:35], off
	v_lshlrev_b64 v[32:33], 12, v[32:33]
	v_lshl_add_u64 v[32:33], s[0:1], 0, v[32:33]
	v_lshl_add_u64 v[50:51], v[32:33], 0, v[160:161]
	global_load_dwordx4 v[32:35], v[50:51], off
	global_load_dwordx4 v[36:39], v[50:51], off offset:64
	global_load_dwordx4 v[40:43], v[50:51], off offset:512
	global_load_dwordx4 v[44:47], v[50:51], off offset:576
	s_waitcnt vmcnt(4)
	v_mul_f32_e32 v52, 0x3fb504f3, v49
	s_waitcnt vmcnt(3)
	v_sub_f32_e32 v33, v33, v48
	v_sub_f32_e32 v32, v32, v48
	v_sub_f32_e32 v35, v35, v48
	v_sub_f32_e32 v34, v34, v48
	v_pk_mul_f32 v[34:35], v[34:35], v[52:53] op_sel_hi:[1,0]
	v_pk_mul_f32 v[32:33], v[32:33], v[52:53] op_sel_hi:[1,0]
	v_pk_fma_f32 v[34:35], v[86:87], v[34:35], v[190:191]
	v_pk_fma_f32 v[32:33], v[84:85], v[32:33], v[192:193]
	v_pk_fma_f32 v[30:31], v[30:31], v[178:179], v[34:35]
	v_pk_fma_f32 v[28:29], v[28:29], v[180:181], v[32:33]
	global_store_dwordx4 v[50:51], v[28:31], off
	s_waitcnt vmcnt(3)
	s_nop 0
	v_sub_f32_e32 v29, v37, v48
	v_sub_f32_e32 v28, v36, v48
	v_sub_f32_e32 v31, v39, v48
	v_sub_f32_e32 v30, v38, v48
	v_pk_mul_f32 v[30:31], v[30:31], v[52:53] op_sel_hi:[1,0]
	v_pk_mul_f32 v[28:29], v[28:29], v[52:53] op_sel_hi:[1,0]
	v_pk_fma_f32 v[30:31], v[74:75], v[30:31], v[186:187]
	v_pk_fma_f32 v[28:29], v[72:73], v[28:29], v[188:189]
	v_pk_fma_f32 v[26:27], v[26:27], v[174:175], v[30:31]
	v_pk_fma_f32 v[24:25], v[24:25], v[176:177], v[28:29]
	global_store_dwordx4 v[50:51], v[24:27], off offset:64
	s_waitcnt vmcnt(3)
	s_nop 0
	v_sub_f32_e32 v25, v41, v48
	v_sub_f32_e32 v24, v40, v48
	v_sub_f32_e32 v27, v43, v48
	v_sub_f32_e32 v26, v42, v48
	v_pk_mul_f32 v[26:27], v[52:53], v[26:27] op_sel_hi:[0,1]
	v_pk_mul_f32 v[24:25], v[52:53], v[24:25] op_sel_hi:[0,1]
	v_pk_fma_f32 v[24:25], v[68:69], v[24:25], v[184:185]
	v_pk_fma_f32 v[26:27], v[70:71], v[26:27], v[182:183]
	v_pk_fma_f32 v[20:21], v[20:21], v[172:173], v[24:25]
	v_pk_fma_f32 v[22:23], v[22:23], v[170:171], v[26:27]
	global_store_dwordx4 v[50:51], v[20:23], off offset:512
	s_waitcnt vmcnt(3)
	s_nop 0
	v_sub_f32_e32 v21, v45, v48
	v_sub_f32_e32 v20, v44, v48
	v_sub_f32_e32 v23, v47, v48
	v_sub_f32_e32 v22, v46, v48
	v_pk_mul_f32 v[22:23], v[52:53], v[22:23] op_sel_hi:[0,1]
	v_pk_mul_f32 v[20:21], v[52:53], v[20:21] op_sel_hi:[0,1]
	v_pk_fma_f32 v[20:21], v[64:65], v[20:21], v[168:169]
	v_pk_fma_f32 v[22:23], v[66:67], v[22:23], v[166:167]
	v_pk_fma_f32 v[16:17], v[16:17], v[164:165], v[20:21]
	v_pk_fma_f32 v[18:19], v[18:19], v[162:163], v[22:23]
	global_store_dwordx4 v[50:51], v[16:19], off offset:576
	s_and_b64 vcc, exec, s[6:7]
	s_cbranch_vccnz .Lmy_epi_w6
	s_sleep 40

.LBB0_1378:
	s_ashr_i32 s25, s76, 3
	s_mul_hi_i32 s35, s25, 0x9000
	s_mul_i32 s25, s25, 0x9000
	s_add_u32 s34, s12, s25
	s_addc_u32 s35, s13, s35
	s_lshl_b32 s25, s76, 8
	v_add_u32_e32 v194, s25, v151
	v_lshl_add_u64 v[128:129], s[20:21], 0, v[160:161]
	v_ashrrev_i32_e32 v195, 31, v194
	global_load_dwordx4 v[162:165], v[128:129], off
	v_lshl_add_u64 v[130:131], s[34:35], 0, v[160:161]
	global_load_dwordx4 v[170:173], v[128:129], off offset:64
	global_load_dwordx4 v[174:177], v[128:129], off offset:512
	global_load_dwordx4 v[178:181], v[130:131], off
	global_load_dwordx4 v[182:185], v[130:131], off offset:64
	global_load_dwordx4 v[232:235], v[128:129], off offset:576
	global_load_dwordx4 v[236:239], v[130:131], off offset:512
	global_load_dwordx4 v[240:243], v[130:131], off offset:576
	v_lshl_add_u64 v[128:129], v[194:195], 3, s[14:15]
	v_lshlrev_b64 v[166:167], 12, v[194:195]
	global_load_dwordx2 v[206:207], v[128:129], off
	v_lshl_add_u64 v[128:129], s[16:17], 0, v[166:167]
	v_lshl_add_u64 v[128:129], v[128:129], 0, v[160:161]
	global_load_dwordx4 v[244:247], v[128:129], off
	global_load_dwordx4 v[248:251], v[128:129], off offset:64
	global_load_dwordx4 v[216:219], v[128:129], off offset:512
	global_load_dwordx4 v[212:215], v[128:129], off offset:576
	v_lshl_add_u64 v[128:129], s[18:19], 0, v[160:161]
	global_load_dwordx4 v[140:143], v[128:129], off
	global_load_dwordx4 v[136:139], v[128:129], off offset:64
	global_load_dwordx4 v[132:135], v[128:129], off offset:512
	s_nop 0
	global_load_dwordx4 v[128:131], v[128:129], off offset:576
	v_lshl_add_u64 v[166:167], s[8:9], 0, v[166:167]
	v_lshl_add_u64 v[198:199], v[166:167], 0, v[160:161]
	s_waitcnt vmcnt(0)
	v_pk_mul_f32 v[168:169], v[172:173], s[58:59] op_sel_hi:[1,0]
	v_pk_mul_f32 v[188:189], v[170:171], s[58:59] op_sel_hi:[1,0]
	v_pk_mul_f32 v[170:171], v[176:177], s[58:59] op_sel_hi:[1,0]
	v_pk_fma_f32 v[176:177], v[178:179], 0.5, 0.5 op_sel_hi:[1,0,0]
	v_pk_mul_f32 v[172:173], v[234:235], s[58:59] op_sel_hi:[1,0]
	v_pk_mul_f32 v[192:193], v[232:233], s[58:59] op_sel_hi:[1,0]
	v_pk_fma_f32 v[178:179], v[184:185], 0.5, 0.5 op_sel_hi:[1,0,0]
	v_pk_fma_f32 v[184:185], v[236:237], 0.5, 0.5 op_sel_hi:[1,0,0]
	v_pk_mul_f32 v[166:167], v[164:165], s[58:59] op_sel_hi:[1,0]
	v_mul_f32_e32 v232, 0x3fb504f3, v207
	v_sub_f32_e32 v235, v245, v206
	v_sub_f32_e32 v234, v244, v206
	v_sub_f32_e32 v237, v247, v206
	v_sub_f32_e32 v236, v246, v206
	v_sub_f32_e32 v213, v213, v206
	v_sub_f32_e32 v212, v212, v206
	v_pk_mul_f32 v[186:187], v[162:163], s[58:59] op_sel_hi:[1,0]
	v_pk_mul_f32 v[190:191], v[174:175], s[58:59] op_sel_hi:[1,0]
	v_pk_fma_f32 v[174:175], v[180:181], 0.5, 0.5 op_sel_hi:[1,0,0]
	v_pk_fma_f32 v[180:181], v[182:183], 0.5, 0.5 op_sel_hi:[1,0,0]
	v_pk_fma_f32 v[182:183], v[238:239], 0.5, 0.5 op_sel_hi:[1,0,0]
	v_pk_fma_f32 v[164:165], v[240:241], 0.5, 0.5 op_sel_hi:[1,0,0]
	v_sub_f32_e32 v239, v249, v206
	v_sub_f32_e32 v238, v248, v206
	v_sub_f32_e32 v241, v251, v206
	v_sub_f32_e32 v240, v250, v206
	v_sub_f32_e32 v217, v217, v206
	v_sub_f32_e32 v216, v216, v206
	v_sub_f32_e32 v219, v219, v206
	v_sub_f32_e32 v218, v218, v206
	v_sub_f32_e32 v207, v215, v206
	v_sub_f32_e32 v206, v214, v206
	v_pk_mul_f32 v[214:215], v[236:237], v[232:233] op_sel_hi:[1,0]
	v_pk_mul_f32 v[234:235], v[234:235], v[232:233] op_sel_hi:[1,0]
	v_pk_mul_f32 v[212:213], v[232:233], v[212:213] op_sel_hi:[0,1]
	v_pk_mul_f32 v[236:237], v[240:241], v[232:233] op_sel_hi:[1,0]
	v_pk_mul_f32 v[238:239], v[238:239], v[232:233] op_sel_hi:[1,0]
	v_pk_mul_f32 v[218:219], v[232:233], v[218:219] op_sel_hi:[0,1]
	v_pk_mul_f32 v[216:217], v[232:233], v[216:217] op_sel_hi:[0,1]
	v_pk_mul_f32 v[206:207], v[232:233], v[206:207] op_sel_hi:[0,1]
	v_pk_fma_f32 v[232:233], v[140:141], v[234:235], v[186:187]
	v_pk_fma_f32 v[214:215], v[142:143], v[214:215], v[166:167]
	v_pk_fma_f32 v[212:213], v[128:129], v[212:213], v[192:193]
	v_pk_fma_f32 v[162:163], v[242:243], 0.5, 0.5 op_sel_hi:[1,0,0]
	v_pk_fma_f32 v[234:235], v[136:137], v[238:239], v[188:189]
	v_pk_fma_f32 v[236:237], v[138:139], v[236:237], v[168:169]
	v_pk_fma_f32 v[216:217], v[132:133], v[216:217], v[190:191]
	v_pk_fma_f32 v[218:219], v[134:135], v[218:219], v[170:171]
	v_pk_fma_f32 v[206:207], v[130:131], v[206:207], v[172:173]
	v_pk_fma_f32 v[126:127], v[126:127], v[174:175], v[214:215]
	v_pk_fma_f32 v[124:125], v[124:125], v[176:177], v[232:233]
	v_pk_fma_f32 v[112:113], v[112:113], v[164:165], v[212:213]
	v_pk_fma_f32 v[122:123], v[122:123], v[178:179], v[236:237]
	v_pk_fma_f32 v[120:121], v[120:121], v[180:181], v[234:235]
	v_pk_fma_f32 v[118:119], v[118:119], v[182:183], v[218:219]
	v_pk_fma_f32 v[116:117], v[116:117], v[184:185], v[216:217]
	v_pk_fma_f32 v[114:115], v[114:115], v[162:163], v[206:207]
	global_store_dwordx4 v[198:199], v[124:127], off
	global_store_dwordx4 v[198:199], v[120:123], off offset:64
	global_store_dwordx4 v[198:199], v[116:119], off offset:512
	global_store_dwordx4 v[198:199], v[112:115], off offset:576
	s_and_b64 vcc, exec, s[6:7]
	s_cbranch_vccnz .Lmy_epi_f0
	s_sleep 40
.Lmy_epi_f0:
	v_add_u32_e32 v212, s25, v227
	v_ashrrev_i32_e32 v213, 31, v212
	v_add_u32_e32 v112, s25, v226
	v_ashrrev_i32_e32 v113, 31, v112
	v_lshlrev_b64 v[206:207], 12, v[112:113]
	v_lshl_add_u64 v[114:115], v[112:113], 3, s[14:15]
	v_lshl_add_u64 v[112:113], s[16:17], 0, v[206:207]
	global_load_dwordx2 v[198:199], v[114:115], off
	v_lshl_add_u64 v[124:125], v[112:113], 0, v[160:161]
	global_load_dwordx4 v[112:115], v[124:125], off
	global_load_dwordx4 v[116:119], v[124:125], off offset:64
	global_load_dwordx4 v[120:123], v[124:125], off offset:512
	s_nop 0
	global_load_dwordx4 v[124:127], v[124:125], off offset:576
	v_lshl_add_u64 v[206:207], s[8:9], 0, v[206:207]
	v_lshl_add_u64 v[206:207], v[206:207], 0, v[160:161]
	v_lshl_add_u64 v[214:215], v[212:213], 3, s[14:15]
	v_lshlrev_b64 v[212:213], 12, v[212:213]
	v_lshl_add_u64 v[216:217], s[16:17], 0, v[212:213]
	v_lshl_add_u64 v[216:217], v[216:217], 0, v[160:161]
	s_waitcnt vmcnt(4)
	v_mul_f32_e32 v218, 0x3fb504f3, v199
	s_waitcnt vmcnt(3)
	v_sub_f32_e32 v113, v113, v198
	v_sub_f32_e32 v112, v112, v198
	v_sub_f32_e32 v115, v115, v198
	v_sub_f32_e32 v114, v114, v198
	s_waitcnt vmcnt(2)
	v_sub_f32_e32 v117, v117, v198
	v_sub_f32_e32 v116, v116, v198
	v_sub_f32_e32 v119, v119, v198
	v_sub_f32_e32 v118, v118, v198
	s_waitcnt vmcnt(1)
	v_sub_f32_e32 v121, v121, v198
	v_sub_f32_e32 v120, v120, v198
	v_sub_f32_e32 v123, v123, v198
	v_sub_f32_e32 v122, v122, v198
	s_waitcnt vmcnt(0)
	v_sub_f32_e32 v125, v125, v198
	v_sub_f32_e32 v124, v124, v198
	v_sub_f32_e32 v127, v127, v198
	v_sub_f32_e32 v126, v126, v198
	v_pk_mul_f32 v[114:115], v[114:115], v[218:219] op_sel_hi:[1,0]
	v_pk_mul_f32 v[112:113], v[112:113], v[218:219] op_sel_hi:[1,0]
	v_pk_mul_f32 v[118:119], v[118:119], v[218:219] op_sel_hi:[1,0]
	v_pk_mul_f32 v[116:117], v[116:117], v[218:219] op_sel_hi:[1,0]
	v_pk_mul_f32 v[122:123], v[218:219], v[122:123] op_sel_hi:[0,1]
	v_pk_mul_f32 v[120:121], v[218:219], v[120:121] op_sel_hi:[0,1]
	v_pk_mul_f32 v[126:127], v[218:219], v[126:127] op_sel_hi:[0,1]
	v_pk_mul_f32 v[124:125], v[218:219], v[124:125] op_sel_hi:[0,1]
	v_pk_fma_f32 v[112:113], v[140:141], v[112:113], v[186:187]
	v_pk_fma_f32 v[114:115], v[142:143], v[114:115], v[166:167]
	v_pk_fma_f32 v[116:117], v[136:137], v[116:117], v[188:189]
	v_pk_fma_f32 v[118:119], v[138:139], v[118:119], v[168:169]
	v_pk_fma_f32 v[120:121], v[132:133], v[120:121], v[190:191]
	v_pk_fma_f32 v[122:123], v[134:135], v[122:123], v[170:171]
	v_pk_fma_f32 v[124:125], v[128:129], v[124:125], v[192:193]
	v_pk_fma_f32 v[126:127], v[130:131], v[126:127], v[172:173]
	v_pk_fma_f32 v[110:111], v[110:111], v[174:175], v[114:115]
	v_pk_fma_f32 v[108:109], v[108:109], v[176:177], v[112:113]
	v_pk_fma_f32 v[106:107], v[106:107], v[178:179], v[118:119]
	v_pk_fma_f32 v[104:105], v[104:105], v[180:181], v[116:117]
	v_pk_fma_f32 v[102:103], v[102:103], v[182:183], v[122:123]
	v_pk_fma_f32 v[100:101], v[100:101], v[184:185], v[120:121]
	v_pk_fma_f32 v[98:99], v[98:99], v[162:163], v[126:127]
	v_pk_fma_f32 v[96:97], v[96:97], v[164:165], v[124:125]
	global_store_dwordx4 v[206:207], v[108:111], off
	global_store_dwordx4 v[206:207], v[104:107], off offset:64
	global_store_dwordx4 v[206:207], v[100:103], off offset:512
	global_store_dwordx4 v[206:207], v[96:99], off offset:576
	s_and_b64 vcc, exec, s[6:7]
	s_cbranch_vccnz .Lmy_epi_f1
	s_sleep 40
.Lmy_epi_f1:
	global_load_dwordx2 v[112:113], v[214:215], off
	global_load_dwordx4 v[96:99], v[216:217], off
	global_load_dwordx4 v[100:103], v[216:217], off offset:64
	global_load_dwordx4 v[104:107], v[216:217], off offset:512
	global_load_dwordx4 v[108:111], v[216:217], off offset:576
	v_add_u32_e32 v114, s25, v228
	v_lshl_add_u64 v[118:119], s[8:9], 0, v[212:213]
	v_ashrrev_i32_e32 v115, 31, v114
	v_lshl_add_u64 v[118:119], v[118:119], 0, v[160:161]
	v_lshl_add_u64 v[116:117], v[114:115], 3, s[14:15]
	v_lshlrev_b64 v[114:115], 12, v[114:115]
	v_lshl_add_u64 v[120:121], s[16:17], 0, v[114:115]
	v_lshl_add_u64 v[120:121], v[120:121], 0, v[160:161]
	s_waitcnt vmcnt(4)
	v_mul_f32_e32 v122, 0x3fb504f3, v113
	s_waitcnt vmcnt(3)
	v_sub_f32_e32 v97, v97, v112
	v_sub_f32_e32 v96, v96, v112
	v_sub_f32_e32 v99, v99, v112
	v_sub_f32_e32 v98, v98, v112
	s_waitcnt vmcnt(2)
	v_sub_f32_e32 v101, v101, v112
	v_sub_f32_e32 v100, v100, v112
	v_sub_f32_e32 v103, v103, v112
	v_sub_f32_e32 v102, v102, v112
	s_waitcnt vmcnt(1)
	v_sub_f32_e32 v105, v105, v112
	v_sub_f32_e32 v104, v104, v112
	v_sub_f32_e32 v107, v107, v112
	v_sub_f32_e32 v106, v106, v112
	s_waitcnt vmcnt(0)
	v_sub_f32_e32 v109, v109, v112
	v_sub_f32_e32 v108, v108, v112
	v_sub_f32_e32 v111, v111, v112
	v_sub_f32_e32 v110, v110, v112
	v_pk_mul_f32 v[98:99], v[98:99], v[122:123] op_sel_hi:[1,0]
	v_pk_mul_f32 v[96:97], v[96:97], v[122:123] op_sel_hi:[1,0]
	v_pk_mul_f32 v[102:103], v[102:103], v[122:123] op_sel_hi:[1,0]
	v_pk_mul_f32 v[100:101], v[100:101], v[122:123] op_sel_hi:[1,0]
	v_pk_mul_f32 v[106:107], v[122:123], v[106:107] op_sel_hi:[0,1]
	v_pk_mul_f32 v[104:105], v[122:123], v[104:105] op_sel_hi:[0,1]
	v_pk_mul_f32 v[110:111], v[122:123], v[110:111] op_sel_hi:[0,1]
	v_pk_mul_f32 v[108:109], v[122:123], v[108:109] op_sel_hi:[0,1]
	v_pk_fma_f32 v[96:97], v[140:141], v[96:97], v[186:187]
	v_pk_fma_f32 v[98:99], v[142:143], v[98:99], v[166:167]
	v_pk_fma_f32 v[100:101], v[136:137], v[100:101], v[188:189]
	v_pk_fma_f32 v[102:103], v[138:139], v[102:103], v[168:169]
	v_pk_fma_f32 v[104:105], v[132:133], v[104:105], v[190:191]
	v_pk_fma_f32 v[106:107], v[134:135], v[106:107], v[170:171]
	v_pk_fma_f32 v[108:109], v[128:129], v[108:109], v[192:193]
	v_pk_fma_f32 v[110:111], v[130:131], v[110:111], v[172:173]
	v_pk_fma_f32 v[94:95], v[94:95], v[174:175], v[98:99]
	v_pk_fma_f32 v[92:93], v[92:93], v[176:177], v[96:97]
	v_pk_fma_f32 v[90:91], v[90:91], v[178:179], v[102:103]
	v_pk_fma_f32 v[88:89], v[88:89], v[180:181], v[100:101]
	v_pk_fma_f32 v[86:87], v[86:87], v[182:183], v[106:107]
	v_pk_fma_f32 v[84:85], v[84:85], v[184:185], v[104:105]
	v_pk_fma_f32 v[82:83], v[82:83], v[162:163], v[110:111]
	v_pk_fma_f32 v[80:81], v[80:81], v[164:165], v[108:109]
	global_store_dwordx4 v[118:119], v[92:95], off
	global_store_dwordx4 v[118:119], v[88:91], off offset:64
	global_store_dwordx4 v[118:119], v[84:87], off offset:512
	global_store_dwordx4 v[118:119], v[80:83], off offset:576
	s_and_b64 vcc, exec, s[6:7]
	s_cbranch_vccnz .Lmy_epi_f2
	s_sleep 40
.Lmy_epi_f2:
	global_load_dwordx2 v[96:97], v[116:117], off
	global_load_dwordx4 v[80:83], v[120:121], off
	global_load_dwordx4 v[84:87], v[120:121], off offset:64
	global_load_dwordx4 v[88:91], v[120:121], off offset:512
	global_load_dwordx4 v[92:95], v[120:121], off offset:576
	v_add_u32_e32 v98, 0x80, v194
	v_lshl_add_u64 v[100:101], s[8:9], 0, v[114:115]
	v_ashrrev_i32_e32 v99, 31, v98
	v_lshl_add_u64 v[100:101], v[100:101], 0, v[160:161]
	v_lshl_add_u64 v[102:103], v[98:99], 3, s[14:15]
	v_lshlrev_b64 v[98:99], 12, v[98:99]
	v_lshl_add_u64 v[104:105], s[16:17], 0, v[98:99]
	v_lshl_add_u64 v[104:105], v[104:105], 0, v[160:161]
	s_waitcnt vmcnt(4)
	v_mul_f32_e32 v106, 0x3fb504f3, v97
	s_waitcnt vmcnt(3)
	v_sub_f32_e32 v81, v81, v96
	v_sub_f32_e32 v80, v80, v96
	v_sub_f32_e32 v83, v83, v96
	v_sub_f32_e32 v82, v82, v96
	s_waitcnt vmcnt(2)
	v_sub_f32_e32 v85, v85, v96
	v_sub_f32_e32 v84, v84, v96
	v_sub_f32_e32 v87, v87, v96
	v_sub_f32_e32 v86, v86, v96
	s_waitcnt vmcnt(1)
	v_sub_f32_e32 v89, v89, v96
	v_sub_f32_e32 v88, v88, v96
	v_sub_f32_e32 v91, v91, v96
	v_sub_f32_e32 v90, v90, v96
	s_waitcnt vmcnt(0)
	v_sub_f32_e32 v93, v93, v96
	v_sub_f32_e32 v92, v92, v96
	v_sub_f32_e32 v95, v95, v96
	v_sub_f32_e32 v94, v94, v96
	v_pk_mul_f32 v[82:83], v[82:83], v[106:107] op_sel_hi:[1,0]
	v_pk_mul_f32 v[80:81], v[80:81], v[106:107] op_sel_hi:[1,0]
	v_pk_mul_f32 v[86:87], v[86:87], v[106:107] op_sel_hi:[1,0]
	v_pk_mul_f32 v[84:85], v[84:85], v[106:107] op_sel_hi:[1,0]
	v_pk_mul_f32 v[90:91], v[106:107], v[90:91] op_sel_hi:[0,1]
	v_pk_mul_f32 v[88:89], v[106:107], v[88:89] op_sel_hi:[0,1]
	v_pk_mul_f32 v[94:95], v[106:107], v[94:95] op_sel_hi:[0,1]
	v_pk_mul_f32 v[92:93], v[106:107], v[92:93] op_sel_hi:[0,1]
	v_pk_fma_f32 v[80:81], v[140:141], v[80:81], v[186:187]
	v_pk_fma_f32 v[82:83], v[142:143], v[82:83], v[166:167]
	v_pk_fma_f32 v[84:85], v[136:137], v[84:85], v[188:189]
	v_pk_fma_f32 v[86:87], v[138:139], v[86:87], v[168:169]
	v_pk_fma_f32 v[88:89], v[132:133], v[88:89], v[190:191]
	v_pk_fma_f32 v[90:91], v[134:135], v[90:91], v[170:171]
	v_pk_fma_f32 v[92:93], v[128:129], v[92:93], v[192:193]
	v_pk_fma_f32 v[94:95], v[130:131], v[94:95], v[172:173]
	v_pk_fma_f32 v[78:79], v[78:79], v[174:175], v[82:83]
	v_pk_fma_f32 v[76:77], v[76:77], v[176:177], v[80:81]
	v_pk_fma_f32 v[74:75], v[74:75], v[178:179], v[86:87]
	v_pk_fma_f32 v[72:73], v[72:73], v[180:181], v[84:85]
	v_pk_fma_f32 v[70:71], v[70:71], v[182:183], v[90:91]
	v_pk_fma_f32 v[68:69], v[68:69], v[184:185], v[88:89]
	v_pk_fma_f32 v[66:67], v[66:67], v[162:163], v[94:95]
	v_pk_fma_f32 v[64:65], v[64:65], v[164:165], v[92:93]
	global_store_dwordx4 v[100:101], v[76:79], off
	global_store_dwordx4 v[100:101], v[72:75], off offset:64
	global_store_dwordx4 v[100:101], v[68:71], off offset:512
	global_store_dwordx4 v[100:101], v[64:67], off offset:576
	s_and_b64 vcc, exec, s[6:7]
	s_cbranch_vccnz .Lmy_epi_f3
	s_sleep 40
.Lmy_epi_f3:
	global_load_dwordx2 v[80:81], v[102:103], off
	global_load_dwordx4 v[64:67], v[104:105], off
	global_load_dwordx4 v[68:71], v[104:105], off offset:64
	global_load_dwordx4 v[72:75], v[104:105], off offset:512
	global_load_dwordx4 v[76:79], v[104:105], off offset:576
	v_add_u32_e32 v82, 0x90, v194
	v_lshl_add_u64 v[86:87], s[8:9], 0, v[98:99]
	v_ashrrev_i32_e32 v83, 31, v82
	v_lshl_add_u64 v[86:87], v[86:87], 0, v[160:161]
	v_lshl_add_u64 v[84:85], v[82:83], 3, s[14:15]
	v_lshlrev_b64 v[82:83], 12, v[82:83]
	v_lshl_add_u64 v[88:89], s[16:17], 0, v[82:83]
	v_lshl_add_u64 v[88:89], v[88:89], 0, v[160:161]
	s_waitcnt vmcnt(4)
	v_mul_f32_e32 v90, 0x3fb504f3, v81
	s_waitcnt vmcnt(3)
	v_sub_f32_e32 v65, v65, v80
	v_sub_f32_e32 v64, v64, v80
	v_sub_f32_e32 v67, v67, v80
	v_sub_f32_e32 v66, v66, v80
	s_waitcnt vmcnt(2)
	v_sub_f32_e32 v69, v69, v80
	v_sub_f32_e32 v68, v68, v80
	v_sub_f32_e32 v71, v71, v80
	v_sub_f32_e32 v70, v70, v80
	s_waitcnt vmcnt(1)
	v_sub_f32_e32 v73, v73, v80
	v_sub_f32_e32 v72, v72, v80
	v_sub_f32_e32 v75, v75, v80
	v_sub_f32_e32 v74, v74, v80
	s_waitcnt vmcnt(0)
	v_sub_f32_e32 v77, v77, v80
	v_sub_f32_e32 v76, v76, v80
	v_sub_f32_e32 v79, v79, v80
	v_sub_f32_e32 v78, v78, v80
	v_pk_mul_f32 v[66:67], v[66:67], v[90:91] op_sel_hi:[1,0]
	v_pk_mul_f32 v[64:65], v[64:65], v[90:91] op_sel_hi:[1,0]
	v_pk_mul_f32 v[70:71], v[70:71], v[90:91] op_sel_hi:[1,0]
	v_pk_mul_f32 v[68:69], v[68:69], v[90:91] op_sel_hi:[1,0]
	v_pk_mul_f32 v[74:75], v[90:91], v[74:75] op_sel_hi:[0,1]
	v_pk_mul_f32 v[72:73], v[90:91], v[72:73] op_sel_hi:[0,1]
	v_pk_mul_f32 v[78:79], v[90:91], v[78:79] op_sel_hi:[0,1]
	v_pk_mul_f32 v[76:77], v[90:91], v[76:77] op_sel_hi:[0,1]
	v_pk_fma_f32 v[64:65], v[140:141], v[64:65], v[186:187]
	v_pk_fma_f32 v[66:67], v[142:143], v[66:67], v[166:167]
	v_pk_fma_f32 v[68:69], v[136:137], v[68:69], v[188:189]
	v_pk_fma_f32 v[70:71], v[138:139], v[70:71], v[168:169]
	v_pk_fma_f32 v[72:73], v[132:133], v[72:73], v[190:191]
	v_pk_fma_f32 v[74:75], v[134:135], v[74:75], v[170:171]
	v_pk_fma_f32 v[76:77], v[128:129], v[76:77], v[192:193]
	v_pk_fma_f32 v[78:79], v[130:131], v[78:79], v[172:173]
	v_pk_fma_f32 v[62:63], v[62:63], v[174:175], v[66:67]
	v_pk_fma_f32 v[60:61], v[60:61], v[176:177], v[64:65]
	v_pk_fma_f32 v[58:59], v[58:59], v[178:179], v[70:71]
	v_pk_fma_f32 v[56:57], v[56:57], v[180:181], v[68:69]
	v_pk_fma_f32 v[54:55], v[54:55], v[182:183], v[74:75]
	v_pk_fma_f32 v[52:53], v[52:53], v[184:185], v[72:73]
	v_pk_fma_f32 v[50:51], v[50:51], v[162:163], v[78:79]
	v_pk_fma_f32 v[48:49], v[48:49], v[164:165], v[76:77]
	global_store_dwordx4 v[86:87], v[60:63], off
	global_store_dwordx4 v[86:87], v[56:59], off offset:64
	global_store_dwordx4 v[86:87], v[52:55], off offset:512
	global_store_dwordx4 v[86:87], v[48:51], off offset:576
	s_and_b64 vcc, exec, s[6:7]
	s_cbranch_vccnz .Lmy_epi_f4
	s_sleep 40
.Lmy_epi_f4:
	global_load_dwordx2 v[64:65], v[84:85], off
	global_load_dwordx4 v[48:51], v[88:89], off
	global_load_dwordx4 v[52:55], v[88:89], off offset:64
	global_load_dwordx4 v[56:59], v[88:89], off offset:512
	global_load_dwordx4 v[60:63], v[88:89], off offset:576
	v_add_u32_e32 v66, 0xa0, v194
	v_lshl_add_u64 v[70:71], s[8:9], 0, v[82:83]
	v_ashrrev_i32_e32 v67, 31, v66
	v_lshl_add_u64 v[70:71], v[70:71], 0, v[160:161]
	v_lshl_add_u64 v[68:69], v[66:67], 3, s[14:15]
	v_lshlrev_b64 v[66:67], 12, v[66:67]
	v_lshl_add_u64 v[72:73], s[16:17], 0, v[66:67]
	v_lshl_add_u64 v[72:73], v[72:73], 0, v[160:161]
	s_waitcnt vmcnt(4)
	v_mul_f32_e32 v74, 0x3fb504f3, v65
	s_waitcnt vmcnt(3)
	v_sub_f32_e32 v49, v49, v64
	v_sub_f32_e32 v48, v48, v64
	v_sub_f32_e32 v51, v51, v64
	v_sub_f32_e32 v50, v50, v64
	s_waitcnt vmcnt(2)
	v_sub_f32_e32 v53, v53, v64
	v_sub_f32_e32 v52, v52, v64
	v_sub_f32_e32 v55, v55, v64
	v_sub_f32_e32 v54, v54, v64
	s_waitcnt vmcnt(1)
	v_sub_f32_e32 v57, v57, v64
	v_sub_f32_e32 v56, v56, v64
	v_sub_f32_e32 v59, v59, v64
	v_sub_f32_e32 v58, v58, v64
	s_waitcnt vmcnt(0)
	v_sub_f32_e32 v61, v61, v64
	v_sub_f32_e32 v60, v60, v64
	v_sub_f32_e32 v63, v63, v64
	v_sub_f32_e32 v62, v62, v64
	v_pk_mul_f32 v[50:51], v[50:51], v[74:75] op_sel_hi:[1,0]
	v_pk_mul_f32 v[48:49], v[48:49], v[74:75] op_sel_hi:[1,0]
	v_pk_mul_f32 v[54:55], v[54:55], v[74:75] op_sel_hi:[1,0]
	v_pk_mul_f32 v[52:53], v[52:53], v[74:75] op_sel_hi:[1,0]
	v_pk_mul_f32 v[58:59], v[74:75], v[58:59] op_sel_hi:[0,1]
	v_pk_mul_f32 v[56:57], v[74:75], v[56:57] op_sel_hi:[0,1]
	v_pk_mul_f32 v[62:63], v[74:75], v[62:63] op_sel_hi:[0,1]
	v_pk_mul_f32 v[60:61], v[74:75], v[60:61] op_sel_hi:[0,1]
	v_pk_fma_f32 v[48:49], v[140:141], v[48:49], v[186:187]
	v_pk_fma_f32 v[50:51], v[142:143], v[50:51], v[166:167]
	v_pk_fma_f32 v[52:53], v[136:137], v[52:53], v[188:189]
	v_pk_fma_f32 v[54:55], v[138:139], v[54:55], v[168:169]
	v_pk_fma_f32 v[56:57], v[132:133], v[56:57], v[190:191]
	v_pk_fma_f32 v[58:59], v[134:135], v[58:59], v[170:171]
	v_pk_fma_f32 v[60:61], v[128:129], v[60:61], v[192:193]
	v_pk_fma_f32 v[62:63], v[130:131], v[62:63], v[172:173]
	v_pk_fma_f32 v[46:47], v[46:47], v[174:175], v[50:51]
	v_pk_fma_f32 v[44:45], v[44:45], v[176:177], v[48:49]
	v_pk_fma_f32 v[42:43], v[42:43], v[178:179], v[54:55]
	v_pk_fma_f32 v[40:41], v[40:41], v[180:181], v[52:53]
	v_pk_fma_f32 v[38:39], v[38:39], v[182:183], v[58:59]
	v_pk_fma_f32 v[36:37], v[36:37], v[184:185], v[56:57]
	v_pk_fma_f32 v[34:35], v[34:35], v[162:163], v[62:63]
	v_pk_fma_f32 v[32:33], v[32:33], v[164:165], v[60:61]
	global_store_dwordx4 v[70:71], v[44:47], off
	global_store_dwordx4 v[70:71], v[40:43], off offset:64
	global_store_dwordx4 v[70:71], v[36:39], off offset:512
	global_store_dwordx4 v[70:71], v[32:35], off offset:576
	s_and_b64 vcc, exec, s[6:7]
	s_cbranch_vccnz .Lmy_epi_f5
	s_sleep 40
.Lmy_epi_f5:
	global_load_dwordx2 v[48:49], v[68:69], off
	global_load_dwordx4 v[32:35], v[72:73], off
	global_load_dwordx4 v[36:39], v[72:73], off offset:64
	global_load_dwordx4 v[40:43], v[72:73], off offset:512
	global_load_dwordx4 v[44:47], v[72:73], off offset:576
	v_add_u32_e32 v50, 0xb0, v194
	v_lshl_add_u64 v[54:55], s[8:9], 0, v[66:67]
	v_ashrrev_i32_e32 v51, 31, v50
	v_lshl_add_u64 v[54:55], v[54:55], 0, v[160:161]
	v_lshl_add_u64 v[52:53], v[50:51], 3, s[14:15]
	v_lshlrev_b64 v[50:51], 12, v[50:51]
	v_lshl_add_u64 v[56:57], s[16:17], 0, v[50:51]
	v_lshl_add_u64 v[56:57], v[56:57], 0, v[160:161]
	s_waitcnt vmcnt(4)
	v_mul_f32_e32 v58, 0x3fb504f3, v49
	s_waitcnt vmcnt(3)
	v_sub_f32_e32 v33, v33, v48
	v_sub_f32_e32 v32, v32, v48
	v_sub_f32_e32 v35, v35, v48
	v_sub_f32_e32 v34, v34, v48
	s_waitcnt vmcnt(2)
	v_sub_f32_e32 v37, v37, v48
	v_sub_f32_e32 v36, v36, v48
	v_sub_f32_e32 v39, v39, v48
	v_sub_f32_e32 v38, v38, v48
	s_waitcnt vmcnt(1)
	v_sub_f32_e32 v41, v41, v48
	v_sub_f32_e32 v40, v40, v48
	v_sub_f32_e32 v43, v43, v48
	v_sub_f32_e32 v42, v42, v48
	s_waitcnt vmcnt(0)
	v_sub_f32_e32 v45, v45, v48
	v_sub_f32_e32 v44, v44, v48
	v_sub_f32_e32 v47, v47, v48
	v_sub_f32_e32 v46, v46, v48
	v_pk_mul_f32 v[34:35], v[34:35], v[58:59] op_sel_hi:[1,0]
	v_pk_mul_f32 v[32:33], v[32:33], v[58:59] op_sel_hi:[1,0]
	v_pk_mul_f32 v[38:39], v[38:39], v[58:59] op_sel_hi:[1,0]
	v_pk_mul_f32 v[36:37], v[36:37], v[58:59] op_sel_hi:[1,0]
	v_pk_mul_f32 v[42:43], v[58:59], v[42:43] op_sel_hi:[0,1]
	v_pk_mul_f32 v[40:41], v[58:59], v[40:41] op_sel_hi:[0,1]
	v_pk_mul_f32 v[46:47], v[58:59], v[46:47] op_sel_hi:[0,1]
	v_pk_mul_f32 v[44:45], v[58:59], v[44:45] op_sel_hi:[0,1]
	v_pk_fma_f32 v[32:33], v[140:141], v[32:33], v[186:187]
	v_pk_fma_f32 v[34:35], v[142:143], v[34:35], v[166:167]
	v_pk_fma_f32 v[36:37], v[136:137], v[36:37], v[188:189]
	v_pk_fma_f32 v[38:39], v[138:139], v[38:39], v[168:169]
	v_pk_fma_f32 v[40:41], v[132:133], v[40:41], v[190:191]
	v_pk_fma_f32 v[42:43], v[134:135], v[42:43], v[170:171]
	v_pk_fma_f32 v[44:45], v[128:129], v[44:45], v[192:193]
	v_pk_fma_f32 v[46:47], v[130:131], v[46:47], v[172:173]
	v_pk_fma_f32 v[30:31], v[30:31], v[174:175], v[34:35]
	v_pk_fma_f32 v[28:29], v[28:29], v[176:177], v[32:33]
	v_pk_fma_f32 v[26:27], v[26:27], v[178:179], v[38:39]
	v_pk_fma_f32 v[24:25], v[24:25], v[180:181], v[36:37]
	v_pk_fma_f32 v[22:23], v[22:23], v[182:183], v[42:43]
	v_pk_fma_f32 v[20:21], v[20:21], v[184:185], v[40:41]
	v_pk_fma_f32 v[18:19], v[18:19], v[162:163], v[46:47]
	v_pk_fma_f32 v[16:17], v[16:17], v[164:165], v[44:45]
	global_store_dwordx4 v[54:55], v[28:31], off
	global_store_dwordx4 v[54:55], v[24:27], off offset:64
	global_store_dwordx4 v[54:55], v[20:23], off offset:512
	global_store_dwordx4 v[54:55], v[16:19], off offset:576
	s_and_b64 vcc, exec, s[6:7]
	s_cbranch_vccnz .Lmy_epi_f6
	s_sleep 40
